# speedup vs baseline: 1.0183x; 1.0183x over previous
; __device__ __forceinline__ void tile_body(bool DIAG, const LAS unsigned char* kb, const LAS unsigned char* vb, int krow, int jm, int hh, int rr, float d00, float m2, float sm2, float M0,
;                                           const bf16x8 (&qf)[4], f32x16 (&O)[4], float& ls) {
;     ...
;     if (!DIAG) { const float base0 = -M0 - sm2 * d00, base1 = base0 + sm2 * 32.0f;
; #pragma unroll
;         for (int r = 0; r < 16; ++r) { const float cr = (float)(16 * (r >> 3) + (r & 7)); s0[r] = fmaf(sm2, cr, base0); s1[r] = fmaf(sm2, cr, base1); }
;     } else {
; #pragma unroll
;         for (int r = 0; r < 16; ++r) { const float cr = (float)(16 * (r >> 3) + (r & 7)); s0[r] = fmaf(-m2, fabsf(d00 - cr), -M0); s1[r] = fmaf(-m2, fabsf(d00 - 32.0f - cr), -M0); }
;     }
;     __builtin_amdgcn_s_setprio(1);
; #pragma unroll
;     for (int t4 = 0; t4 < 4; ++t4) s0 = __builtin_amdgcn_mfma_f32_32x32x16_bf16(kf[0][t4], qf[t4], s0, 0, 0, 0);
; #pragma unroll
;     for (int t4 = 0; t4 < 4; ++t4) s1 = __builtin_amdgcn_mfma_f32_32x32x16_bf16(kf[1][t4], qf[t4], s1, 0, 0, 0);
;     __builtin_amdgcn_s_setprio(0);
;     __builtin_amdgcn_sched_barrier(0);
;     float a = 0.f;
; #pragma unroll
;     for (int sb = 0; sb < 2; ++sb) {
;         bf16x8 vf[4][2];
; #pragma unroll
;         for (int cb = 0; cb < 4; ++cb)
; #pragma unroll
;             for (int k2 = 0; k2 < 2; ++k2) { const int e = 32 * cb + rr, c = 2 * (2 * sb + k2) + hh;
;                 vf[cb][k2] = *(const LAS bf16x8*)(vb + e * 128 + ((c ^ ((e >> 1) & 7)) * 16)); }
;         f32x16& s = sb ? s1 : s0;
; #pragma unroll
;         for (int r = 0; r < 16; ++r) { s[r] = __builtin_amdgcn_exp2f(s[r]); a += s[r]; }
;         bf16x8 pk[2];
; #pragma unroll
;         for (int k2 = 0; k2 < 2; ++k2) { u32x4 w; w.x = cvtpk(s[8 * k2 + 0], s[8 * k2 + 1]); w.y = cvtpk(s[8 * k2 + 2], s[8 * k2 + 3]); w.z = cvtpk(s[8 * k2 + 4], s[8 * k2 + 5]); w.w = cvtpk(s[8 * k2 + 6], s[8 * k2 + 7]);
;             pk[k2] = __builtin_bit_cast(bf16x8, w); }
;         __builtin_amdgcn_s_setprio(1);
; #pragma unroll
;         for (int cb = 0; cb < 4; ++cb)
; #pragma unroll
;             for (int k2 = 0; k2 < 2; ++k2) O[cb] = __builtin_amdgcn_mfma_f32_32x32x16_bf16(pk[k2], vf[cb][k2], O[cb], 0, 0, 0);
;         __builtin_amdgcn_s_setprio(0);
;         if (sb == 0) __builtin_amdgcn_sched_barrier(0);
;     }
;     ls += a;
.Llin0:
	v_cndmask_b32_e64 v78, -v171, v171, s[16:17]
	v_fma_f32 v80, -v78, v184, -v201
	v_fmamk_f32 v64, v78, 0x42000000, v80
	v_add_f32_e32 v81, v78, v80
	v_add_f32_e32 v65, v78, v64
	v_fma_f32 v82, v78, s80, v80
	v_fma_f32 v83, v78, s81, v80
	v_fma_f32 v66, v78, s80, v64
	v_fma_f32 v67, v78, s81, v64
	v_fma_f32 v84, v78, s66, v80
	v_fma_f32 v85, v78, s67, v80
	v_fma_f32 v68, v78, s66, v64
	v_fma_f32 v69, v78, s67, v64
	v_fma_f32 v86, v78, s74, v80
	v_fma_f32 v87, v78, s75, v80
	v_fma_f32 v70, v78, s74, v64
	v_fma_f32 v71, v78, s75, v64
	v_fma_f32 v88, v78, s34, v80
	v_fma_f32 v89, v78, s35, v80
	v_fma_f32 v72, v78, s34, v64
	v_fma_f32 v73, v78, s35, v64
	v_fma_f32 v90, v78, s96, v80
	v_fma_f32 v91, v78, s97, v80
	v_fma_f32 v74, v78, s96, v64
	v_fma_f32 v75, v78, s97, v64
	v_fma_f32 v92, v78, s52, v80
	v_fma_f32 v93, v78, s53, v80
	v_fma_f32 v76, v78, s52, v64
	v_fma_f32 v77, v78, s53, v64
	v_fma_f32 v95, v78, s55, v80
	v_fma_f32 v94, v78, s54, v80
	v_fma_f32 v79, v78, s55, v64
	v_fma_f32 v78, v78, s54, v64
.LBB0_1308:
	s_waitcnt lgkmcnt(0)
	v_mfma_f32_32x32x16_bf16 v[64:79], v[130:133], v[98:101], v[64:79]
	v_mfma_f32_32x32x16_bf16 v[80:95], v[114:117], v[98:101], v[80:95]
	v_mfma_f32_32x32x16_bf16 v[64:79], v[134:137], v[102:105], v[64:79]
	v_mfma_f32_32x32x16_bf16 v[80:95], v[118:121], v[102:105], v[80:95]
	v_mfma_f32_32x32x16_bf16 v[64:79], v[138:141], v[106:109], v[64:79]
	v_mfma_f32_32x32x16_bf16 v[80:95], v[122:125], v[106:109], v[80:95]
	v_mfma_f32_32x32x16_bf16 v[64:79], v[142:145], v[110:113], v[64:79]
	v_mfma_f32_32x32x16_bf16 v[80:95], v[126:129], v[110:113], v[80:95]
	ds_read_b128 v[114:117], v176 offset:16384
	ds_read_b128 v[118:121], v176 offset:20480
	ds_read_b128 v[122:125], v177 offset:16384
	ds_read_b128 v[126:129], v177 offset:20480
	ds_read_b128 v[130:133], v176 offset:24576
	ds_read_b128 v[134:137], v176 offset:28672
	ds_read_b128 v[138:141], v177 offset:24576
	ds_read_b128 v[142:145], v177 offset:28672
	v_exp_f32_e32 v173, v80
	v_exp_f32_e32 v184, v81
	v_exp_f32_e32 v192, v82
	v_exp_f32_e32 v218, v83
	v_exp_f32_e32 v219, v84
	v_exp_f32_e32 v220, v85
	v_exp_f32_e32 v221, v86
	v_exp_f32_e32 v222, v87
	v_exp_f32_e32 v223, v88
	v_exp_f32_e32 v224, v89
	v_exp_f32_e32 v225, v90
	v_exp_f32_e32 v217, v91
	v_exp_f32_e32 v226, v92
	v_exp_f32_e32 v227, v93
	v_exp_f32_e32 v228, v94
	v_exp_f32_e32 v229, v95
	v_cvt_pk_bf16_f32 v80, v173, v184
	v_cvt_pk_bf16_f32 v81, v192, v218
	v_cvt_pk_bf16_f32 v82, v219, v220
	v_cvt_pk_bf16_f32 v83, v221, v222
	v_cvt_pk_bf16_f32 v84, v223, v224
	v_cvt_pk_bf16_f32 v85, v225, v217
	v_cvt_pk_bf16_f32 v86, v226, v227
	v_cvt_pk_bf16_f32 v87, v228, v229
	s_waitcnt lgkmcnt(0)
	v_mfma_f32_32x32x16_bf16 v[32:47], v[80:83], v[114:117], v[32:47]
	v_mfma_f32_32x32x16_bf16 v[48:63], v[80:83], v[118:121], v[48:63]
	v_mfma_f32_32x32x16_bf16 v[16:31], v[80:83], v[130:133], v[16:31]
	v_mfma_f32_32x32x16_bf16 v[0:15], v[80:83], v[134:137], v[0:15]
	v_mfma_f32_32x32x16_bf16 v[32:47], v[84:87], v[122:125], v[32:47]
	v_mfma_f32_32x32x16_bf16 v[48:63], v[84:87], v[126:129], v[48:63]
	v_mfma_f32_32x32x16_bf16 v[16:31], v[84:87], v[138:141], v[16:31]
	v_mfma_f32_32x32x16_bf16 v[0:15], v[84:87], v[142:145], v[0:15]
	ds_read_b128 v[80:83], v178 offset:16384
	ds_read_b128 v[84:87], v178 offset:20480
	ds_read_b128 v[88:91], v179 offset:16384
	ds_read_b128 v[92:95], v179 offset:20480
	ds_read_b128 v[114:117], v178 offset:24576
	ds_read_b128 v[118:121], v178 offset:28672
	ds_read_b128 v[122:125], v179 offset:24576
	ds_read_b128 v[126:129], v179 offset:28672
	v_exp_f32_e32 v130, v64
	v_exp_f32_e32 v131, v65
	v_exp_f32_e32 v132, v66
	v_exp_f32_e32 v133, v67
	v_exp_f32_e32 v134, v68
	v_exp_f32_e32 v135, v69
	v_exp_f32_e32 v136, v70
	v_exp_f32_e32 v137, v71
	v_exp_f32_e32 v72, v72
	v_exp_f32_e32 v73, v73
	v_exp_f32_e32 v74, v74
	v_exp_f32_e32 v75, v75
	v_exp_f32_e32 v76, v76
	v_exp_f32_e32 v77, v77
	v_exp_f32_e32 v78, v78
	v_exp_f32_e32 v79, v79
	v_cvt_pk_bf16_f32 v64, v130, v131
	v_cvt_pk_bf16_f32 v65, v132, v133
	v_cvt_pk_bf16_f32 v66, v134, v135
	v_cvt_pk_bf16_f32 v67, v136, v137
	v_cvt_pk_bf16_f32 v68, v72, v73
	v_cvt_pk_bf16_f32 v69, v74, v75
	v_cvt_pk_bf16_f32 v70, v76, v77
	v_cvt_pk_bf16_f32 v71, v78, v79
	s_waitcnt lgkmcnt(0)
	v_mfma_f32_32x32x16_bf16 v[32:47], v[64:67], v[80:83], v[32:47]
	v_mfma_f32_32x32x16_bf16 v[48:63], v[64:67], v[84:87], v[48:63]
	v_mfma_f32_32x32x16_bf16 v[16:31], v[64:67], v[114:117], v[16:31]
	v_mfma_f32_32x32x16_bf16 v[0:15], v[64:67], v[118:121], v[0:15]
	v_mfma_f32_32x32x16_bf16 v[32:47], v[68:71], v[88:91], v[32:47]
	v_mfma_f32_32x32x16_bf16 v[48:63], v[68:71], v[92:95], v[48:63]
	v_mfma_f32_32x32x16_bf16 v[16:31], v[68:71], v[122:125], v[16:31]
	v_mfma_f32_32x32x16_bf16 v[0:15], v[68:71], v[126:129], v[0:15]
	v_add_f32_e32 v64, 0, v173
	v_add_f32_e32 v64, v184, v64
	v_add_f32_e32 v64, v192, v64
	v_add_f32_e32 v64, v218, v64
	v_add_f32_e32 v64, v219, v64
	v_add_f32_e32 v64, v220, v64
	v_add_f32_e32 v64, v221, v64
	v_add_f32_e32 v64, v222, v64
	v_add_f32_e32 v64, v223, v64
	v_add_f32_e32 v64, v224, v64
	v_add_f32_e32 v64, v225, v64
	v_add_f32_e32 v64, v217, v64
	v_add_f32_e32 v64, v226, v64
	v_add_f32_e32 v64, v227, v64
	v_add_f32_e32 v64, v228, v64
	v_add_f32_e32 v64, v229, v64
	v_add_f32_e32 v64, v130, v64
	v_add_f32_e32 v64, v131, v64
	v_add_f32_e32 v64, v132, v64
	v_add_f32_e32 v64, v133, v64
	v_add_f32_e32 v64, v134, v64
	v_add_f32_e32 v64, v135, v64
	v_add_f32_e32 v64, v136, v64
	v_add_f32_e32 v64, v137, v64
	v_add_f32_e32 v64, v72, v64
	v_add_f32_e32 v64, v73, v64
	v_add_f32_e32 v64, v74, v64
	v_add_f32_e32 v64, v75, v64
	v_add_f32_e32 v64, v76, v64
	v_add_f32_e32 v64, v77, v64
	v_add_f32_e32 v64, v78, v64
	v_add_f32_e32 v64, v79, v64
	v_add_f32_e32 v197, v197, v64

; __device__ __forceinline__ void tile_body(bool DIAG, const LAS unsigned char* kb, const LAS unsigned char* vb, int krow, int jm, int hh, int rr, float d00, float m2, float sm2, float M0,
;                                           const bf16x8 (&qf)[4], f32x16 (&O)[4], float& ls) {
;     ...
;     } else {
; #pragma unroll
;         for (int r = 0; r < 16; ++r) { const float cr = (float)(16 * (r >> 3) + (r & 7)); s0[r] = fmaf(-m2, fabsf(d00 - cr), -M0); s1[r] = fmaf(-m2, fabsf(d00 - 32.0f - cr), -M0); }
;     }
.Ldiag0:
	v_pk_add_f32 v[66:67], v[184:185], s[56:57] op_sel_hi:[0,1]
	v_pk_add_f32 v[82:83], v[184:185], s[38:39] op_sel_hi:[0,1]
	v_add_f32_e32 v65, -1.0, v184
	v_add_f32_e32 v64, 0xc2000000, v184
	v_pk_add_f32 v[70:71], v[184:185], s[58:59] op_sel_hi:[0,1]
	v_pk_add_f32 v[74:75], v[184:185], s[60:61] op_sel_hi:[0,1]
	v_pk_add_f32 v[80:81], v[184:185], s[64:65] op_sel_hi:[0,1]
	v_pk_add_f32 v[84:85], v[184:185], s[30:31] op_sel_hi:[0,1]
	v_and_b32_e32 v67, 0x7fffffff, v67
	v_and_b32_e32 v66, 0x7fffffff, v66
	v_and_b32_e32 v83, 0x7fffffff, v83
	v_and_b32_e32 v82, 0x7fffffff, v82
	v_mov_b32_e32 v153, v152
	v_mov_b32_e32 v173, v172
	v_add_f32_e32 v192, -1.0, v64
	v_pk_add_f32 v[68:69], v[64:65], s[56:57] op_sel_hi:[0,1]
	v_pk_add_f32 v[72:73], v[64:65], s[58:59] op_sel_hi:[0,1]
	v_pk_add_f32 v[76:77], v[64:65], s[60:61] op_sel_hi:[0,1]
	v_pk_add_f32 v[78:79], v[184:185], s[62:63] op_sel_hi:[0,1]
	v_pk_add_f32 v[218:219], v[64:65], s[62:63] op_sel_hi:[0,1]
	v_pk_add_f32 v[220:221], v[64:65], s[64:65] op_sel_hi:[0,1]
	v_pk_add_f32 v[222:223], v[64:65], s[38:39] op_sel_hi:[0,1]
	v_and_b32_e32 v71, 0x7fffffff, v71
	v_and_b32_e32 v70, 0x7fffffff, v70
	v_and_b32_e32 v75, 0x7fffffff, v75
	v_and_b32_e32 v74, 0x7fffffff, v74
	v_and_b32_e32 v81, 0x7fffffff, v81
	v_and_b32_e32 v80, 0x7fffffff, v80
	v_and_b32_e32 v85, 0x7fffffff, v85
	v_and_b32_e32 v84, 0x7fffffff, v84
	v_and_b32_e32 v224, 0x7fffffff, v184
	v_and_b32_e32 v225, 0x7fffffff, v65
	v_pk_fma_f32 v[92:93], v[172:173], v[82:83], v[152:153]
	v_pk_fma_f32 v[82:83], v[172:173], v[66:67], v[152:153]
	v_pk_add_f32 v[66:67], v[64:65], s[30:31] op_sel_hi:[0,1]
	v_and_b32_e32 v79, 0x7fffffff, v79
	v_and_b32_e32 v78, 0x7fffffff, v78
	v_pk_fma_f32 v[94:95], v[172:173], v[84:85], v[152:153]
	v_pk_fma_f32 v[90:91], v[172:173], v[80:81], v[152:153]
	v_pk_fma_f32 v[86:87], v[172:173], v[74:75], v[152:153]
	v_pk_fma_f32 v[84:85], v[172:173], v[70:71], v[152:153]
	v_pk_fma_f32 v[80:81], v[174:175], v[224:225], v[154:155]
	v_and_b32_e32 v225, 0x7fffffff, v69
	v_and_b32_e32 v224, 0x7fffffff, v68
	v_and_b32_e32 v69, 0x7fffffff, v73
	v_and_b32_e32 v68, 0x7fffffff, v72
	v_and_b32_e32 v71, 0x7fffffff, v77
	v_and_b32_e32 v70, 0x7fffffff, v76
	v_and_b32_e32 v73, 0x7fffffff, v219
	v_and_b32_e32 v72, 0x7fffffff, v218
	v_and_b32_e32 v75, 0x7fffffff, v221
	v_and_b32_e32 v74, 0x7fffffff, v220
	v_and_b32_e32 v77, 0x7fffffff, v223
	v_and_b32_e32 v76, 0x7fffffff, v222
	v_and_b32_e32 v67, 0x7fffffff, v67
	v_and_b32_e32 v66, 0x7fffffff, v66
	v_and_b32_e32 v64, 0x7fffffff, v64
	v_and_b32_e32 v65, 0x7fffffff, v192
	v_pk_fma_f32 v[88:89], v[172:173], v[78:79], v[152:153]
	v_pk_fma_f32 v[78:79], v[172:173], v[66:67], v[152:153]
	v_pk_fma_f32 v[76:77], v[172:173], v[76:77], v[152:153]
	v_pk_fma_f32 v[74:75], v[172:173], v[74:75], v[152:153]
	v_pk_fma_f32 v[72:73], v[172:173], v[72:73], v[152:153]
	v_pk_fma_f32 v[70:71], v[172:173], v[70:71], v[152:153]
	v_pk_fma_f32 v[68:69], v[172:173], v[68:69], v[152:153]
	v_pk_fma_f32 v[66:67], v[172:173], v[224:225], v[152:153]
	v_pk_fma_f32 v[64:65], v[174:175], v[64:65], v[154:155]
	s_branch .LBB0_1308
